# grid-barrier release words polled with four loads in flight (rolling window) instead of load-wait-sleep; original loop kept as the timeout fallback; on v61
# baseline (speedup 1.0000x reference)
; __device__ __forceinline__ unsigned xb_ld(unsigned* p)              { return __hip_atomic_load(p, __ATOMIC_RELAXED, __HIP_MEMORY_SCOPE_AGENT); }
; __device__ __forceinline__ unsigned xb_add(unsigned* p, unsigned v) { return __hip_atomic_fetch_add(p, v, __ATOMIC_RELAXED, __HIP_MEMORY_SCOPE_AGENT); }
; #define XB_SPIN(cond, bar) do { unsigned _sp = 0; while (cond) { __builtin_amdgcn_s_sleep(6); \
;     if ((++_sp & 255u) == 0u) { if (xb_ld(&(bar)[XB_TMO])) break; if (_sp > XB_SPIN_CAP) { atomicAdd(&(bar)[XB_TMO], 1u); break; } } } } while (0)
; __device__ __forceinline__ void xcd_barrier(const XcdBarrier& b) {
;     ...
;         const unsigned old = xb_add(&bar[XB_XSUB(b.x)], 1u);
;         const unsigned gen = old / nloc;
;         if (old + 1u == (gen + 1u) * nloc) {
;             __builtin_amdgcn_fence(__ATOMIC_RELEASE, "agent");
;             asm volatile("s_waitcnt vmcnt(0)" ::: "memory");
;             const unsigned og = xb_add(&bar[XB_TOP], 1u);
;             const unsigned tg = og / nx;
;             if (og + 1u == (tg + 1u) * nx) xb_add(&bar[XB_TOPGEN], 1u);
;             else XB_SPIN(xb_ld(&bar[XB_TOPGEN]) == tg, bar);
;             __builtin_amdgcn_fence(__ATOMIC_ACQUIRE, "agent");
;             xb_add(&bar[XB_XGEN(b.x)], 1u);
;             asm volatile("s_waitcnt vmcnt(0)" ::: "memory");
;         } else {
;             XB_SPIN(xb_ld(&bar[XB_XGEN(b.x)]) == gen, bar);
.LBB0_104:
	s_lshl_b32 s4, s13, 8
	s_mov_b32 s5, 0
	v_lshl_add_u64 v[2:3], v[0:1], 0, s[4:5]
	v_add_co_u32_e32 v8, vcc, 0x28d01000, v2
	v_mov_b32_e32 v5, 1
	s_nop 0
	v_addc_co_u32_e32 v9, vcc, 0, v3, vcc
	global_atomic_add v5, v[8:9], v5, off offset:1024 sc0
	v_cvt_f32_u32_e32 v7, v6
	v_sub_u32_e32 v8, 0, v6
	s_mov_b64 s[4:5], 0x28d00000
	v_lshl_add_u64 v[2:3], v[2:3], 0, s[4:5]
	v_rcp_iflag_f32_e32 v7, v7
	s_nop 0
	v_mul_f32_e32 v7, 0x4f7ffffe, v7
	v_cvt_u32_f32_e32 v7, v7
	v_mul_lo_u32 v8, v8, v7
	v_mul_hi_u32 v8, v7, v8
	v_add_u32_e32 v7, v7, v8
	s_waitcnt vmcnt(0)
	v_mul_hi_u32 v7, v5, v7
	v_mul_lo_u32 v9, v7, v6
	v_add_u32_e32 v8, 1, v5
	v_sub_u32_e32 v5, v5, v9
	v_add_u32_e32 v10, 1, v7
	v_cmp_ge_u32_e32 vcc, v5, v6
	v_sub_u32_e32 v9, v5, v6
	s_nop 0
	v_cndmask_b32_e32 v7, v7, v10, vcc
	v_cndmask_b32_e32 v5, v5, v9, vcc
	v_add_u32_e32 v9, 1, v7
	v_cmp_ge_u32_e32 vcc, v5, v6
	s_nop 1
	v_cndmask_b32_e32 v5, v7, v9, vcc
	v_mad_u64_u32 v[6:7], s[4:5], v6, v5, v[6:7]
	v_cmp_ne_u32_e32 vcc, v8, v6
	s_and_saveexec_b64 s[4:5], vcc
	s_xor_b64 s[4:5], exec, s[4:5]
	s_cbranch_execz .LBB0_117
	v_add_co_u32_e32 v6, vcc, 0x2000, v2
	s_nop 1
	v_addc_co_u32_e32 v7, vcc, 0, v3, vcc
	s_waitcnt lgkmcnt(0)
	global_load_dword v4, v[6:7], off offset:1024 sc1
	s_waitcnt vmcnt(0)
	v_cmp_eq_u32_e32 vcc, v4, v5
	s_and_saveexec_b64 s[6:7], vcc
	s_cbranch_execz .LBB0_116
	s_mov_b64 s[8:9], 0x2400
	v_lshl_add_u64 v[2:3], v[2:3], 0, s[8:9]
	s_mov_b64 s[8:9], 0x28d00200
	v_lshl_add_u64 v[0:1], v[0:1], 0, s[8:9]
	s_mov_b32 s13, 1
	s_mov_b64 s[8:9], 0
	global_load_dword v4, v[2:3], off sc1
	s_sleep 2
	global_load_dword v60, v[2:3], off sc1
	s_sleep 2
	global_load_dword v61, v[2:3], off sc1
	s_sleep 2
	global_load_dword v62, v[2:3], off sc1
	s_movk_i32 s13, 0x4000
.Lfs0_loop:
	s_waitcnt vmcnt(3)
	v_cmp_ne_u32_e32 vcc, v4, v5
	s_cbranch_vccnz .Lfs0_out
	global_load_dword v4, v[2:3], off sc1
	s_waitcnt vmcnt(3)
	v_cmp_ne_u32_e32 vcc, v60, v5
	s_cbranch_vccnz .Lfs0_out
	global_load_dword v60, v[2:3], off sc1
	s_waitcnt vmcnt(3)
	v_cmp_ne_u32_e32 vcc, v61, v5
	s_cbranch_vccnz .Lfs0_out
	global_load_dword v61, v[2:3], off sc1
	s_waitcnt vmcnt(3)
	v_cmp_ne_u32_e32 vcc, v62, v5
	s_cbranch_vccnz .Lfs0_out
	global_load_dword v62, v[2:3], off sc1
	s_sub_u32 s13, s13, 1
	s_cmp_lg_u32 s13, 0
	s_cbranch_scc1 .Lfs0_loop
	s_waitcnt vmcnt(0)
	s_mov_b32 s13, 1
	s_branch .LBB0_108
.Lfs0_out:
	s_waitcnt vmcnt(0)
	s_branch .LBB0_116

; __device__ __forceinline__ unsigned xb_ld(unsigned* p)              { return __hip_atomic_load(p, __ATOMIC_RELAXED, __HIP_MEMORY_SCOPE_AGENT); }
; __device__ __forceinline__ unsigned xb_add(unsigned* p, unsigned v) { return __hip_atomic_fetch_add(p, v, __ATOMIC_RELAXED, __HIP_MEMORY_SCOPE_AGENT); }
; #define XB_SPIN(cond, bar) do { unsigned _sp = 0; while (cond) { __builtin_amdgcn_s_sleep(6); \
;     if ((++_sp & 255u) == 0u) { if (xb_ld(&(bar)[XB_TMO])) break; if (_sp > XB_SPIN_CAP) { atomicAdd(&(bar)[XB_TMO], 1u); break; } } } } while (0)
; __device__ __forceinline__ void xcd_barrier(const XcdBarrier& b) {
;     ...
;         if (old + 1u == (gen + 1u) * nloc) {
;             __builtin_amdgcn_fence(__ATOMIC_RELEASE, "agent");
;             asm volatile("s_waitcnt vmcnt(0)" ::: "memory");
;             const unsigned og = xb_add(&bar[XB_TOP], 1u);
;             const unsigned tg = og / nx;
;             if (og + 1u == (tg + 1u) * nx) xb_add(&bar[XB_TOPGEN], 1u);
;             else XB_SPIN(xb_ld(&bar[XB_TOPGEN]) == tg, bar);
;             __builtin_amdgcn_fence(__ATOMIC_ACQUIRE, "agent");
.LBB0_117:
	s_andn2_saveexec_b64 s[4:5], s[4:5]
	s_cbranch_execz .LBB0_133
	v_add_co_u32_e32 v6, vcc, 0x28d03000, v0
	buffer_wbl2 sc1
	s_waitcnt lgkmcnt(0)
	s_waitcnt vmcnt(0)
	v_addc_co_u32_e32 v7, vcc, 0, v1, vcc
	v_mov_b32_e32 v5, 1
	global_atomic_add v5, v[6:7], v5, off offset:1024 sc0
	v_cvt_f32_u32_e32 v6, v4
	v_sub_u32_e32 v8, 0, v4
	s_mov_b64 s[4:5], 0x28d03500
	s_mov_b64 s[6:7], -1
	v_rcp_iflag_f32_e32 v6, v6
	s_nop 0
	v_mul_f32_e32 v6, 0x4f7ffffe, v6
	v_cvt_u32_f32_e32 v9, v6
	v_lshl_add_u64 v[6:7], v[0:1], 0, s[4:5]
	v_mul_lo_u32 v8, v8, v9
	v_mul_hi_u32 v8, v9, v8
	v_add_u32_e32 v8, v9, v8
	s_waitcnt vmcnt(0)
	v_mul_hi_u32 v8, v5, v8
	v_mul_lo_u32 v10, v8, v4
	v_add_u32_e32 v9, 1, v5
	v_sub_u32_e32 v5, v5, v10
	v_add_u32_e32 v11, 1, v8
	v_cmp_ge_u32_e32 vcc, v5, v4
	v_sub_u32_e32 v10, v5, v4
	s_nop 0
	v_cndmask_b32_e32 v8, v8, v11, vcc
	v_cndmask_b32_e32 v5, v5, v10, vcc
	v_add_u32_e32 v10, 1, v8
	v_cmp_ge_u32_e32 vcc, v5, v4
	s_nop 1
	v_cndmask_b32_e32 v8, v8, v10, vcc
	v_mad_u64_u32 v[4:5], s[4:5], v4, v8, v[4:5]
	v_cmp_ne_u32_e32 vcc, v9, v4
	s_and_saveexec_b64 s[4:5], vcc
	s_cbranch_execz .LBB0_130
	global_load_dword v4, v[6:7], off sc1
	s_mov_b64 s[8:9], 0
	s_waitcnt vmcnt(0)
	v_cmp_eq_u32_e32 vcc, v4, v8
	s_and_saveexec_b64 s[6:7], vcc
	s_cbranch_execz .LBB0_129
	s_mov_b64 s[8:9], 0x28d00200
	v_lshl_add_u64 v[4:5], v[0:1], 0, s[8:9]
	s_mov_b32 s13, 1
	s_mov_b64 s[8:9], 0
	global_load_dword v0, v[6:7], off sc1
	s_sleep 2
	global_load_dword v60, v[6:7], off sc1
	s_sleep 2
	global_load_dword v61, v[6:7], off sc1
	s_sleep 2
	global_load_dword v62, v[6:7], off sc1
	s_movk_i32 s13, 0x4000
.Lfs1_loop:
	s_waitcnt vmcnt(3)
	v_cmp_ne_u32_e32 vcc, v0, v8
	s_cbranch_vccnz .Lfs1_out
	global_load_dword v0, v[6:7], off sc1
	s_waitcnt vmcnt(3)
	v_cmp_ne_u32_e32 vcc, v60, v8
	s_cbranch_vccnz .Lfs1_out
	global_load_dword v60, v[6:7], off sc1
	s_waitcnt vmcnt(3)
	v_cmp_ne_u32_e32 vcc, v61, v8
	s_cbranch_vccnz .Lfs1_out
	global_load_dword v61, v[6:7], off sc1
	s_waitcnt vmcnt(3)
	v_cmp_ne_u32_e32 vcc, v62, v8
	s_cbranch_vccnz .Lfs1_out
	global_load_dword v62, v[6:7], off sc1
	s_sub_u32 s13, s13, 1
	s_cmp_lg_u32 s13, 0
	s_cbranch_scc1 .Lfs1_loop
	s_waitcnt vmcnt(0)
	s_mov_b32 s13, 1
	s_branch .LBB0_122
.Lfs1_out:
	s_waitcnt vmcnt(0)
	s_mov_b64 s[8:9], 0
	s_branch .LBB0_129

; __device__ __forceinline__ unsigned xb_ld(unsigned* p)              { return __hip_atomic_load(p, __ATOMIC_RELAXED, __HIP_MEMORY_SCOPE_AGENT); }
; __device__ __forceinline__ unsigned xb_add(unsigned* p, unsigned v) { return __hip_atomic_fetch_add(p, v, __ATOMIC_RELAXED, __HIP_MEMORY_SCOPE_AGENT); }
; #define XB_SPIN(cond, bar) do { unsigned _sp = 0; while (cond) { __builtin_amdgcn_s_sleep(6); \
;     if ((++_sp & 255u) == 0u) { if (xb_ld(&(bar)[XB_TMO])) break; if (_sp > XB_SPIN_CAP) { atomicAdd(&(bar)[XB_TMO], 1u); break; } } } } while (0)
; __device__ __forceinline__ void xcd_barrier(const XcdBarrier& b) {
;     ...
;         const unsigned old = xb_add(&bar[XB_XSUB(b.x)], 1u);
;         const unsigned gen = old / nloc;
;         if (old + 1u == (gen + 1u) * nloc) {
;             __builtin_amdgcn_fence(__ATOMIC_RELEASE, "agent");
;             asm volatile("s_waitcnt vmcnt(0)" ::: "memory");
;             const unsigned og = xb_add(&bar[XB_TOP], 1u);
;             const unsigned tg = og / nx;
;             if (og + 1u == (tg + 1u) * nx) xb_add(&bar[XB_TOPGEN], 1u);
;             else XB_SPIN(xb_ld(&bar[XB_TOPGEN]) == tg, bar);
;             __builtin_amdgcn_fence(__ATOMIC_ACQUIRE, "agent");
;             xb_add(&bar[XB_XGEN(b.x)], 1u);
;             asm volatile("s_waitcnt vmcnt(0)" ::: "memory");
;         } else {
;             XB_SPIN(xb_ld(&bar[XB_XGEN(b.x)]) == gen, bar);
.LBB0_294:
	s_lshl_b32 s38, s38, 8
	v_lshl_add_u64 v[2:3], v[0:1], 0, s[38:39]
	v_add_co_u32_e32 v8, vcc, 0x28d01000, v2
	v_cvt_f32_u32_e32 v7, v6
	s_nop 0
	v_addc_co_u32_e32 v9, vcc, 0, v3, vcc
	global_atomic_add v5, v[8:9], v195, off offset:1024 sc0
	v_rcp_iflag_f32_e32 v7, v7
	v_sub_u32_e32 v8, 0, v6
	s_mov_b64 s[4:5], 0x28d00000
	v_lshl_add_u64 v[2:3], v[2:3], 0, s[4:5]
	v_mul_f32_e32 v7, 0x4f7ffffe, v7
	v_cvt_u32_f32_e32 v7, v7
	v_mul_lo_u32 v8, v8, v7
	v_mul_hi_u32 v8, v7, v8
	v_add_u32_e32 v7, v7, v8
	s_waitcnt vmcnt(0)
	v_mul_hi_u32 v7, v5, v7
	v_mul_lo_u32 v9, v7, v6
	v_add_u32_e32 v8, 1, v5
	v_sub_u32_e32 v5, v5, v9
	v_add_u32_e32 v10, 1, v7
	v_cmp_ge_u32_e32 vcc, v5, v6
	v_sub_u32_e32 v9, v5, v6
	s_nop 0
	v_cndmask_b32_e32 v7, v7, v10, vcc
	v_cndmask_b32_e32 v5, v5, v9, vcc
	v_add_u32_e32 v9, 1, v7
	v_cmp_ge_u32_e32 vcc, v5, v6
	s_nop 1
	v_cndmask_b32_e32 v5, v7, v9, vcc
	v_mad_u64_u32 v[6:7], s[4:5], v6, v5, v[6:7]
	v_cmp_ne_u32_e32 vcc, v8, v6
	s_and_saveexec_b64 s[4:5], vcc
	s_xor_b64 s[4:5], exec, s[4:5]
	s_cbranch_execz .LBB0_307
	v_add_co_u32_e32 v6, vcc, 0x2000, v2
	s_nop 1
	v_addc_co_u32_e32 v7, vcc, 0, v3, vcc
	s_waitcnt lgkmcnt(0)
	global_load_dword v4, v[6:7], off offset:1024 sc1
	s_waitcnt vmcnt(0)
	v_cmp_eq_u32_e32 vcc, v4, v5
	s_and_saveexec_b64 s[6:7], vcc
	s_cbranch_execz .LBB0_306
	s_mov_b64 s[8:9], 0x2400
	v_lshl_add_u64 v[2:3], v[2:3], 0, s[8:9]
	s_mov_b64 s[8:9], 0x28d00200
	v_lshl_add_u64 v[0:1], v[0:1], 0, s[8:9]
	s_mov_b32 s24, 1
	s_mov_b64 s[8:9], 0
	global_load_dword v4, v[2:3], off sc1
	s_sleep 2
	global_load_dword v60, v[2:3], off sc1
	s_sleep 2
	global_load_dword v61, v[2:3], off sc1
	s_sleep 2
	global_load_dword v62, v[2:3], off sc1
	s_movk_i32 s24, 0x4000
.Lfs4_loop:
	s_waitcnt vmcnt(3)
	v_cmp_ne_u32_e32 vcc, v4, v5
	s_cbranch_vccnz .Lfs4_out
	global_load_dword v4, v[2:3], off sc1
	s_waitcnt vmcnt(3)
	v_cmp_ne_u32_e32 vcc, v60, v5
	s_cbranch_vccnz .Lfs4_out
	global_load_dword v60, v[2:3], off sc1
	s_waitcnt vmcnt(3)
	v_cmp_ne_u32_e32 vcc, v61, v5
	s_cbranch_vccnz .Lfs4_out
	global_load_dword v61, v[2:3], off sc1
	s_waitcnt vmcnt(3)
	v_cmp_ne_u32_e32 vcc, v62, v5
	s_cbranch_vccnz .Lfs4_out
	global_load_dword v62, v[2:3], off sc1
	s_sub_u32 s24, s24, 1
	s_cmp_lg_u32 s24, 0
	s_cbranch_scc1 .Lfs4_loop
	s_waitcnt vmcnt(0)
	s_mov_b32 s24, 1
	s_branch .LBB0_298

; __device__ __forceinline__ unsigned xb_ld(unsigned* p)              { return __hip_atomic_load(p, __ATOMIC_RELAXED, __HIP_MEMORY_SCOPE_AGENT); }
; __device__ __forceinline__ unsigned xb_add(unsigned* p, unsigned v) { return __hip_atomic_fetch_add(p, v, __ATOMIC_RELAXED, __HIP_MEMORY_SCOPE_AGENT); }
; #define XB_SPIN(cond, bar) do { unsigned _sp = 0; while (cond) { __builtin_amdgcn_s_sleep(6); \
;     if ((++_sp & 255u) == 0u) { if (xb_ld(&(bar)[XB_TMO])) break; if (_sp > XB_SPIN_CAP) { atomicAdd(&(bar)[XB_TMO], 1u); break; } } } } while (0)
; __device__ __forceinline__ void xcd_barrier(const XcdBarrier& b) {
;     ...
;         if (old + 1u == (gen + 1u) * nloc) {
;             __builtin_amdgcn_fence(__ATOMIC_RELEASE, "agent");
;             asm volatile("s_waitcnt vmcnt(0)" ::: "memory");
;             const unsigned og = xb_add(&bar[XB_TOP], 1u);
;             const unsigned tg = og / nx;
;             if (og + 1u == (tg + 1u) * nx) xb_add(&bar[XB_TOPGEN], 1u);
;             else XB_SPIN(xb_ld(&bar[XB_TOPGEN]) == tg, bar);
;             __builtin_amdgcn_fence(__ATOMIC_ACQUIRE, "agent");
.LBB0_307:
	s_andn2_saveexec_b64 s[4:5], s[4:5]
	s_cbranch_execz .LBB0_323
	v_add_co_u32_e32 v6, vcc, 0x28d03000, v0
	buffer_wbl2 sc1
	s_waitcnt lgkmcnt(0)
	s_waitcnt vmcnt(0)
	v_addc_co_u32_e32 v7, vcc, 0, v1, vcc
	global_atomic_add v5, v[6:7], v195, off offset:1024 sc0
	v_cvt_f32_u32_e32 v6, v4
	v_sub_u32_e32 v7, 0, v4
	s_mov_b64 s[6:7], -1
	v_rcp_iflag_f32_e32 v6, v6
	s_nop 0
	v_mul_f32_e32 v6, 0x4f7ffffe, v6
	v_cvt_u32_f32_e32 v6, v6
	v_mul_lo_u32 v7, v7, v6
	v_mul_hi_u32 v7, v6, v7
	v_add_u32_e32 v6, v6, v7
	s_waitcnt vmcnt(0)
	v_mul_hi_u32 v6, v5, v6
	v_mul_lo_u32 v7, v6, v4
	v_sub_u32_e32 v7, v5, v7
	v_cmp_ge_u32_e32 vcc, v7, v4
	v_add_u32_e32 v8, 1, v6
	s_nop 0
	v_cndmask_b32_e32 v6, v6, v8, vcc
	v_sub_u32_e32 v8, v7, v4
	v_cndmask_b32_e32 v7, v7, v8, vcc
	v_cmp_ge_u32_e32 vcc, v7, v4
	v_add_u32_e32 v7, 1, v6
	s_nop 0
	v_cndmask_b32_e32 v8, v6, v7, vcc
	v_add_u32_e32 v6, 1, v5
	v_mad_u64_u32 v[4:5], s[4:5], v4, v8, v[4:5]
	s_mov_b64 s[4:5], 0x28d03500
	v_cmp_ne_u32_e32 vcc, v6, v4
	v_lshl_add_u64 v[4:5], v[0:1], 0, s[4:5]
	s_and_saveexec_b64 s[4:5], vcc
	s_cbranch_execz .LBB0_320
	global_load_dword v6, v[4:5], off sc1
	s_mov_b64 s[8:9], 0
	s_waitcnt vmcnt(0)
	v_cmp_eq_u32_e32 vcc, v6, v8
	s_and_saveexec_b64 s[6:7], vcc
	s_cbranch_execz .LBB0_319
	s_mov_b64 s[8:9], 0x28d00200
	v_lshl_add_u64 v[6:7], v[0:1], 0, s[8:9]
	s_mov_b32 s22, 1
	s_mov_b64 s[8:9], 0
	global_load_dword v0, v[4:5], off sc1
	s_sleep 2
	global_load_dword v60, v[4:5], off sc1
	s_sleep 2
	global_load_dword v61, v[4:5], off sc1
	s_sleep 2
	global_load_dword v62, v[4:5], off sc1
	s_movk_i32 s22, 0x4000
.Lfs5_loop:
	s_waitcnt vmcnt(3)
	v_cmp_ne_u32_e32 vcc, v0, v8
	s_cbranch_vccnz .Lfs5_out
	global_load_dword v0, v[4:5], off sc1
	s_waitcnt vmcnt(3)
	v_cmp_ne_u32_e32 vcc, v60, v8
	s_cbranch_vccnz .Lfs5_out
	global_load_dword v60, v[4:5], off sc1
	s_waitcnt vmcnt(3)
	v_cmp_ne_u32_e32 vcc, v61, v8
	s_cbranch_vccnz .Lfs5_out
	global_load_dword v61, v[4:5], off sc1
	s_waitcnt vmcnt(3)
	v_cmp_ne_u32_e32 vcc, v62, v8
	s_cbranch_vccnz .Lfs5_out
	global_load_dword v62, v[4:5], off sc1
	s_sub_u32 s22, s22, 1
	s_cmp_lg_u32 s22, 0
	s_cbranch_scc1 .Lfs5_loop
	s_waitcnt vmcnt(0)
	s_mov_b32 s22, 1
	s_branch .LBB0_312
